# attn0: 20-slot 160 KiB LDS ring, next step's K/V tiles and Q prefetched during the current step, one barrier per step
# speedup vs baseline: 1.0083x; 1.0083x over previous
.LBB0_431:
	v_writelane_b32 v255, s76, 19
	s_and_b32 s33, s7, -2
	v_writelane_b32 v255, s75, 20
	s_lshr_b32 s77, 0x80, s33
	s_lshl_b32 s75, s71, 10
	s_sub_i32 s76, 12, s33
	s_add_i32 s77, s77, -1
	s_add_i32 s75, s75, 0
	s_add_u32 s4, s0, 0x19000000
	s_addc_u32 s5, s1, 0
	v_writelane_b32 v255, s7, 21
	s_and_b64 s[2:3], exec, s[2:3]
	s_cselect_b32 s3, s83, s5
	v_writelane_b32 v255, s82, 22
	s_cselect_b32 s2, s82, s4
	s_add_u32 s4, s0, 0xb00000
	v_writelane_b32 v255, s83, 23
	v_writelane_b32 v255, s4, 24
	s_addc_u32 s4, s1, 0
	s_cmp_gt_i32 s71, 3
	v_lshlrev_b32_e32 v2, 1, v243
	v_lshrrev_b32_e32 v4, 5, v243
	s_cselect_b64 s[92:93], -1, 0
	s_lshl_b32 s6, s71, 4
	v_writelane_b32 v255, s4, 25
	v_and_b32_e32 v8, 8, v2
	v_lshlrev_b32_e32 v2, 3, v4
	v_lshlrev_b32_e32 v4, 4, v243
	v_mov_b32_e32 v5, v0
	s_ashr_i32 s7, s6, 31
	s_add_i32 s4, s6, 0x7fffffc0
	v_lshl_add_u64 v[6:7], s[2:3], 0, v[4:5]
	s_lshl_b32 s2, s71, 5
	v_writelane_b32 v255, s6, 26
	s_and_b32 s78, s2, 0x60
	s_lshl_b32 s78, s78, 5
	s_lshl_b32 s2, -1, s76
	v_writelane_b32 v255, s7, 27
	s_not_b32 s73, s2
	v_readlane_b32 s2, v255, 17
	v_lshrrev_b32_e32 v1, 1, v242
	s_and_b32 s4, s4, 0x7fffffe0
	v_mov_b32_e32 v3, v0
	v_readlane_b32 s3, v255, 18
	v_and_b32_e32 v150, 31, v242
	v_and_b32_e32 v1, 4, v1
	v_and_b32_e32 v9, 19, v242
	v_lshl_add_u64 v[116:117], v[6:7], 0, s[78:79]
	v_lshl_add_u64 v[118:119], s[2:3], 0, v[4:5]
	v_lshl_add_u64 v[120:121], s[18:19], 0, v[2:3]
	s_cmp_gt_i32 s10, 0
	v_or_b32_e32 v3, 2, v2
	v_or_b32_e32 v4, 3, v2
	v_or_b32_e32 v5, 4, v2
	v_or_b32_e32 v6, 5, v2
	v_or_b32_e32 v7, 6, v2
	v_or_b32_e32 v10, 7, v2
	v_or_b32_e32 v11, 16, v2
	s_waitcnt lgkmcnt(3)
	v_or_b32_e32 v12, 17, v2
	s_waitcnt lgkmcnt(2)
	v_or_b32_e32 v13, 18, v2
	s_waitcnt lgkmcnt(0)
	v_or_b32_e32 v14, 19, v2
	v_or_b32_e32 v15, 20, v2
	v_or_b32_e32 v16, 21, v2
	v_or_b32_e32 v17, 22, v2
	v_or_b32_e32 v18, 23, v2
	v_or_b32_e32 v19, 1, v2
	v_or_b32_e32 v151, s4, v150
	v_writelane_b32 v255, s10, 28
	s_cselect_b64 s[88:89], -1, 0
	v_lshl_add_u32 v152, v243, 4, 0
	v_cmp_gt_u32_e64 s[2:3], 32, v243
	v_cmp_gt_u32_e64 s[4:5], v2, v150
	v_cmp_lt_u32_e64 s[6:7], v2, v150
	v_cmp_gt_u32_e64 s[8:9], v3, v150
	v_cmp_gt_u32_e64 s[10:11], v4, v150
	v_cmp_gt_u32_e64 s[12:13], v5, v150
	v_cmp_gt_u32_e64 s[14:15], v6, v150
	v_cmp_gt_u32_e64 s[16:17], v7, v150
	v_cmp_gt_u32_e64 s[18:19], v10, v150
	v_cmp_gt_u32_e64 s[20:21], v11, v150
	v_cmp_gt_u32_e64 s[22:23], v12, v150
	v_cmp_gt_u32_e64 s[24:25], v13, v150
	v_cmp_gt_u32_e64 s[26:27], v14, v150
	v_cmp_gt_u32_e64 s[28:29], v15, v150
	v_cmp_gt_u32_e64 s[30:31], v16, v150
	v_cmp_gt_u32_e64 s[34:35], v17, v150
	v_cmp_gt_u32_e64 s[36:37], v18, v150
	v_cmp_lt_u32_e64 s[38:39], v19, v150
	v_cmp_lt_u32_e64 s[40:41], v3, v150
	v_cmp_lt_u32_e64 s[42:43], v4, v150
	v_cmp_lt_u32_e64 s[44:45], v5, v150
	v_cmp_lt_u32_e64 s[46:47], v6, v150
	v_cmp_lt_u32_e64 s[48:49], v7, v150
	v_cmp_lt_u32_e64 s[50:51], v10, v150
	v_cmp_lt_u32_e64 s[52:53], v11, v150
	v_cmp_lt_u32_e64 s[54:55], v12, v150
	v_cmp_lt_u32_e64 s[56:57], v13, v150
	v_cmp_lt_u32_e64 s[58:59], v14, v150
	v_cmp_lt_u32_e64 s[60:61], v15, v150
	v_cmp_lt_u32_e64 s[62:63], v16, v150
	v_cmp_lt_u32_e64 s[64:65], v17, v150
	v_cmp_lt_u32_e64 s[66:67], v18, v150
	v_or3_b32 v153, v1, v9, v8
	s_lshl_b32 s86, s70, 6
	v_lshlrev_b32_e32 v122, 1, v2
	v_and_b32_e32 v251, 31, v243
	v_lshlrev_b32_e32 v251, 2, v251
	v_add_u32_e32 v251, 0x23f80, v251
	ds_read_b32 v250, v251
	s_waitcnt lgkmcnt(0)
	s_branch .LBB0_433

.LBB0_437:
	s_lshl_b32 s98, s74, 4
	s_add_i32 s98, s98, s72
	s_lshl_b32 s98, s98, 19
	s_mov_b32 s99, 0
	s_lshl_b32 s69, s70, 6
	s_and_b32 s94, s69, 64
	s_lshl_b64 s[82:83], s[78:79], 1
	s_lshl_b32 s69, s72, 2
	v_readlane_b32 s72, v255, 24
	v_lshl_add_u64 v[142:143], v[118:119], 0, s[98:99]
	v_lshl_add_u64 v[144:145], v[120:121], 0, s[82:83]
	s_add_u32 s82, s72, s69
	v_readlane_b32 s69, v255, 25
	v_or_b32_e32 v123, s87, v150
	s_addc_u32 s83, s69, 0
	s_lshl_b32 s78, s68, 1
	s_mov_b32 s95, 0
	s_mov_b32 s84, 0
	s_and_b32 s74, s94, s77
	s_add_i32 s68, s94, -4
	s_cmp_eq_u32 s74, 0
	s_cselect_b32 s68, s94, s68
	s_cselect_b32 s101, 0, 0x20000
	s_or_b32 s69, s94, 7
	s_sub_i32 s69, s69, s68
	s_add_i32 s69, s69, 1
	v_mov_b32_e32 v1, s68
	s_waitcnt lgkmcnt(0)
	s_barrier
	v_mad_i64_i32 v[2:3], vcc, s78, v1, v[140:141]
.La0_dma0:
	s_add_i32 vcc_lo, s75, s101
	s_mov_b32 vcc_hi, m0
	s_mov_b32 m0, vcc_lo
	s_nop 0
	global_load_lds_dwordx4 v[2:3], off
	s_mov_b32 m0, vcc_hi
	s_add_i32 s101, s101, 0x2000
	s_add_i32 s68, s101, 0xfffd8000
	s_cmp_ge_i32 s101, 0x28000
	s_cselect_b32 s101, s68, s101
	v_lshl_add_u64 v[2:3], v[2:3], 0, s[78:79]
	s_add_i32 s69, s69, -1
	s_cmp_lg_u32 s69, 0
	s_cbranch_scc1 .La0_dma0
	s_add_i32 s68, s94, s71
	s_lshl_b32 s98, s68, 12
	s_mov_b32 s99, 0
	v_lshl_add_u64 v[2:3], v[142:143], 0, s[98:99]
	global_load_dwordx4 v[92:95], v[2:3], off
	global_load_dwordx4 v[88:91], v[2:3], off offset:1024
	global_load_dwordx4 v[84:87], v[2:3], off offset:2048
	global_load_dwordx4 v[80:83], v[2:3], off offset:3072
	s_branch .LBB0_439
.LBB0_438:
	s_or_b64 exec, exec, s[68:69]
	s_add_i32 s95, s95, 1
	s_cmp_eq_u32 s95, 8
	s_cbranch_scc1 .LBB0_432
.LBB0_439:
	s_lshl_b32 s72, s95, 3
	s_add_i32 s72, s72, s94
	s_and_b32 s74, s72, s77
	s_add_i32 s72, s72, s71
	s_lshl_b32 s68, s72, 5
	s_ashr_i32 s69, s68, s76
	s_and_b32 s68, s68, s73
	v_or_b32_e32 v1, s68, v150
	v_lshlrev_b32_e32 v1, s33, v1
	s_add_i32 s69, s69, s87
	v_add_u32_e32 v2, s69, v1
	v_ashrrev_i32_e32 v3, 31, v2
	v_lshlrev_b64 v[4:5], 11, v[2:3]
	v_lshlrev_b64 v[2:3], 6, v[2:3]
	v_lshl_add_u64 v[148:149], v[144:145], 0, v[4:5]
	v_lshl_add_u64 v[146:147], s[82:83], 0, v[2:3]
	s_cmp_eq_u32 s95, 0
	s_cbranch_scc1 .La0_w0
	s_waitcnt vmcnt(9)
	s_branch .La0_w1

.La0_w1:
	s_waitcnt lgkmcnt(0)
	s_barrier
	s_and_b64 vcc, exec, s[88:89]
	s_cbranch_vccz .La0_nopv
	global_load_dword v154, v[146:147], off
	global_load_dwordx2 v[138:139], v[148:149], off
	global_load_dwordx2 v[136:137], v[148:149], off offset:16
	global_load_dwordx2 v[134:135], v[148:149], off offset:32
	global_load_dwordx2 v[132:133], v[148:149], off offset:48
	global_load_dwordx2 v[130:131], v[148:149], off offset:64
	global_load_dwordx2 v[128:129], v[148:149], off offset:80
	global_load_dwordx2 v[126:127], v[148:149], off offset:96
	global_load_dwordx2 v[124:125], v[148:149], off offset:112
	s_branch .La0_pvd
.La0_nopv:
	v_mov_b32_e32 v154, 0
.La0_pvd:
	s_cmp_eq_u32 s95, 7
	s_cbranch_scc1 .La0_nopf
	s_sub_i32 s68, s72, s71
	s_add_i32 s68, s68, 8
	v_mov_b32_e32 v1, s68
	s_add_i32 s101, s84, 0x10000
	s_add_i32 s68, s101, 0xfffd8000
	s_cmp_ge_i32 s101, 0x28000
	s_cselect_b32 s101, s68, s101
	s_mov_b32 s69, 8
	v_mad_i64_i32 v[2:3], vcc, s78, v1, v[140:141]
.La0_dma1:
	s_add_i32 vcc_lo, s75, s101
	s_mov_b32 vcc_hi, m0
	s_mov_b32 m0, vcc_lo
	s_nop 0
	global_load_lds_dwordx4 v[2:3], off
	s_mov_b32 m0, vcc_hi
	s_add_i32 s101, s101, 0x2000
	s_add_i32 s68, s101, 0xfffd8000
	s_cmp_ge_i32 s101, 0x28000
	s_cselect_b32 s101, s68, s101
	v_lshl_add_u64 v[2:3], v[2:3], 0, s[78:79]
	s_add_i32 s69, s69, -1
	s_cmp_lg_u32 s69, 0
	s_cbranch_scc1 .La0_dma1
.La0_nopf:
	s_lshl_b32 s68, s71, 13
	s_add_i32 s68, s68, s84
	s_add_i32 s68, s68, 0xffff8000
	s_add_i32 s69, s68, 0x28000
	s_cmp_lt_i32 s68, 0
	s_cselect_b32 s68, s69, s68
	s_add_i32 s69, s68, 0xfffd8000
	s_cmp_ge_i32 s68, 0x28000
	s_cselect_b32 s100, s69, s68
	s_add_i32 s84, s84, 0x10000
	s_add_i32 s68, s84, 0xfffd8000
	s_cmp_ge_i32 s84, 0x28000
	s_cselect_b32 s84, s68, s84
	s_add_i32 s85, s74, s71
	v_mov_b32_e32 v68, v238
	v_xor_b32_e32 v155, 32, v238
	v_and_b32_e32 v156, 64, v238
	v_add_u32_e32 v156, 64, v156
	v_cmp_lt_i32_e32 vcc, v155, v156
	s_nop 1
	v_cndmask_b32_e32 v157, v238, v155, vcc
	v_lshlrev_b32_e32 v157, 2, v157
	s_cmp_lt_i32 s85, 4
	s_cbranch_scc1 .La0_miss0
	s_add_i32 s68, s100, 0x0
	s_add_i32 s69, s68, 0xfffd8000
	s_cmp_ge_i32 s68, 0x28000
	s_cselect_b32 s68, s69, s68
	v_add_u32_e32 v158, s68, v152
	ds_read_b128 v[48:51], v158
	ds_read_b128 v[52:55], v158 offset:1024
	ds_read_b128 v[56:59], v158 offset:2048
	ds_read_b128 v[60:63], v158 offset:3072
	s_waitcnt lgkmcnt(3)
	v_mfma_f32_32x32x16_bf16 v[160:175], v[48:51], v[92:95], 0
	s_waitcnt lgkmcnt(2)
	v_mfma_f32_32x32x16_bf16 v[160:175], v[52:55], v[88:91], v[160:175]
	s_waitcnt lgkmcnt(1)
	v_mfma_f32_32x32x16_bf16 v[160:175], v[56:59], v[84:87], v[160:175]
	s_waitcnt lgkmcnt(0)
	v_mfma_f32_32x32x16_bf16 v[160:175], v[60:63], v[80:83], v[160:175]
	s_branch .La0_have0

.La0_have0:
	s_cmp_lt_i32 s85, 3
	s_cbranch_scc1 .La0_miss1
	s_add_i32 s68, s100, 0x2000
	s_add_i32 s69, s68, 0xfffd8000
	s_cmp_ge_i32 s68, 0x28000
	s_cselect_b32 s68, s69, s68
	v_add_u32_e32 v158, s68, v152
	ds_read_b128 v[224:227], v158
	ds_read_b128 v[228:231], v158 offset:1024
	ds_read_b128 v[2:5], v158 offset:2048
	ds_read_b128 v[8:11], v158 offset:3072
	s_waitcnt lgkmcnt(3)
	v_mfma_f32_32x32x16_bf16 v[176:191], v[224:227], v[92:95], 0
	s_waitcnt lgkmcnt(2)
	v_mfma_f32_32x32x16_bf16 v[176:191], v[228:231], v[88:91], v[176:191]
	s_waitcnt lgkmcnt(1)
	v_mfma_f32_32x32x16_bf16 v[176:191], v[2:5], v[84:87], v[176:191]
	s_waitcnt lgkmcnt(0)
	v_mfma_f32_32x32x16_bf16 v[176:191], v[8:11], v[80:83], v[176:191]
	s_branch .La0_have1

.La0_have1:
	s_cmp_lt_i32 s85, 2
	s_cbranch_scc1 .La0_miss2
	s_add_i32 s68, s100, 0x4000
	s_add_i32 s69, s68, 0xfffd8000
	s_cmp_ge_i32 s68, 0x28000
	s_cselect_b32 s68, s69, s68
	v_add_u32_e32 v158, s68, v152
	ds_read_b128 v[48:51], v158
	ds_read_b128 v[52:55], v158 offset:1024
	ds_read_b128 v[56:59], v158 offset:2048
	ds_read_b128 v[60:63], v158 offset:3072
	s_waitcnt lgkmcnt(3)
	v_mfma_f32_32x32x16_bf16 v[192:207], v[48:51], v[92:95], 0
	s_waitcnt lgkmcnt(2)
	v_mfma_f32_32x32x16_bf16 v[192:207], v[52:55], v[88:91], v[192:207]
	s_waitcnt lgkmcnt(1)
	v_mfma_f32_32x32x16_bf16 v[192:207], v[56:59], v[84:87], v[192:207]
	s_waitcnt lgkmcnt(0)
	v_mfma_f32_32x32x16_bf16 v[192:207], v[60:63], v[80:83], v[192:207]
	s_branch .La0_have2

.La0_have2:
	s_cmp_lt_i32 s85, 1
	s_cbranch_scc1 .La0_miss3
	s_add_i32 s68, s100, 0x6000
	s_add_i32 s69, s68, 0xfffd8000
	s_cmp_ge_i32 s68, 0x28000
	s_cselect_b32 s68, s69, s68
	v_add_u32_e32 v158, s68, v152
	ds_read_b128 v[224:227], v158
	ds_read_b128 v[228:231], v158 offset:1024
	ds_read_b128 v[2:5], v158 offset:2048
	ds_read_b128 v[8:11], v158 offset:3072
	s_waitcnt lgkmcnt(3)
	v_mfma_f32_32x32x16_bf16 v[208:223], v[224:227], v[92:95], 0
	s_waitcnt lgkmcnt(2)
	v_mfma_f32_32x32x16_bf16 v[208:223], v[228:231], v[88:91], v[208:223]
	s_waitcnt lgkmcnt(1)
	v_mfma_f32_32x32x16_bf16 v[208:223], v[2:5], v[84:87], v[208:223]
	s_waitcnt lgkmcnt(0)
	v_mfma_f32_32x32x16_bf16 v[208:223], v[8:11], v[80:83], v[208:223]
	s_branch .La0_have3

.La0_have3:
	s_add_i32 s68, s100, 0x8000
	s_add_i32 s69, s68, 0xfffd8000
	s_cmp_ge_i32 s68, 0x28000
	s_cselect_b32 s68, s69, s68
	v_add_u32_e32 v158, s68, v152
	ds_read_b128 v[48:51], v158
	ds_read_b128 v[52:55], v158 offset:1024
	ds_read_b128 v[56:59], v158 offset:2048
	ds_read_b128 v[60:63], v158 offset:3072
	s_waitcnt lgkmcnt(3)
	v_mfma_f32_32x32x16_bf16 v[96:111], v[48:51], v[92:95], 0
	s_waitcnt lgkmcnt(2)
	v_mfma_f32_32x32x16_bf16 v[96:111], v[52:55], v[88:91], v[96:111]
	s_waitcnt lgkmcnt(1)
	v_mfma_f32_32x32x16_bf16 v[96:111], v[56:59], v[84:87], v[96:111]
	s_waitcnt lgkmcnt(0)
	v_mfma_f32_32x32x16_bf16 v[96:111], v[60:63], v[80:83], v[96:111]
	s_cmp_eq_u32 s95, 7
	s_cbranch_scc1 .La0_noq
	s_add_i32 s68, s72, 8
	s_lshl_b32 s98, s68, 12
	s_mov_b32 s99, 0
	v_lshl_add_u64 v[64:65], v[142:143], 0, s[98:99]
	global_load_dwordx4 v[92:95], v[64:65], off
	global_load_dwordx4 v[88:91], v[64:65], off offset:1024
	global_load_dwordx4 v[84:87], v[64:65], off offset:2048
	global_load_dwordx4 v[80:83], v[64:65], off offset:3072
.La0_noq:
	s_nop 7
	s_nop 4
	v_cndmask_b32_e64 v160, v160, v239, s[6:7]
	v_cndmask_b32_e64 v161, v161, v239, s[38:39]
	v_cndmask_b32_e64 v162, v162, v239, s[40:41]
	v_cndmask_b32_e64 v163, v163, v239, s[42:43]
	v_cndmask_b32_e64 v164, v164, v239, s[44:45]
	v_cndmask_b32_e64 v165, v165, v239, s[46:47]
	v_cndmask_b32_e64 v166, v166, v239, s[48:49]
	v_cndmask_b32_e64 v167, v167, v239, s[50:51]
	v_cndmask_b32_e64 v168, v168, v239, s[52:53]
	v_cndmask_b32_e64 v169, v169, v239, s[54:55]
	v_cndmask_b32_e64 v170, v170, v239, s[56:57]
	v_cndmask_b32_e64 v171, v171, v239, s[58:59]
	v_cndmask_b32_e64 v172, v172, v239, s[60:61]
	v_cndmask_b32_e64 v173, v173, v239, s[62:63]
	v_cndmask_b32_e64 v174, v174, v239, s[64:65]
	v_cndmask_b32_e64 v175, v175, v239, s[66:67]
	v_cndmask_b32_e64 v96, v96, v239, s[4:5]
	v_cndmask_b32_e64 v97, v239, v97, s[6:7]
	v_cndmask_b32_e64 v98, v98, v239, s[8:9]
	v_cndmask_b32_e64 v99, v99, v239, s[10:11]
	v_cndmask_b32_e64 v100, v100, v239, s[12:13]
	v_cndmask_b32_e64 v101, v101, v239, s[14:15]
	v_cndmask_b32_e64 v102, v102, v239, s[16:17]
	v_cndmask_b32_e64 v103, v103, v239, s[18:19]
	v_cndmask_b32_e64 v104, v104, v239, s[20:21]
	v_cndmask_b32_e64 v105, v105, v239, s[22:23]
	v_cndmask_b32_e64 v106, v106, v239, s[24:25]
	v_cndmask_b32_e64 v107, v107, v239, s[26:27]
	v_cndmask_b32_e64 v108, v108, v239, s[28:29]
	v_cndmask_b32_e64 v109, v109, v239, s[30:31]
	v_cndmask_b32_e64 v110, v110, v239, s[34:35]
	v_cndmask_b32_e64 v111, v111, v239, s[36:37]
	v_max3_f32 v12, v160, v161, v162
	v_max3_f32 v13, v163, v164, v165
	v_max3_f32 v14, v166, v167, v168
	v_max3_f32 v15, v169, v170, v171
	v_max3_f32 v12, v12, v172, v173
	v_max3_f32 v13, v13, v174, v175
	v_max3_f32 v14, v14, v176, v177
	v_max3_f32 v15, v15, v178, v179
	v_max3_f32 v12, v12, v180, v181
	v_max3_f32 v13, v13, v182, v183
	v_max3_f32 v14, v14, v184, v185
	v_max3_f32 v15, v15, v186, v187
	v_max3_f32 v12, v12, v188, v189
	v_max3_f32 v13, v13, v190, v191
	v_max3_f32 v14, v14, v192, v193
	v_max3_f32 v15, v15, v194, v195
	v_max3_f32 v12, v12, v196, v197
	v_max3_f32 v13, v13, v198, v199
	v_max3_f32 v14, v14, v200, v201
	v_max3_f32 v15, v15, v202, v203
	v_max3_f32 v12, v12, v204, v205
	v_max3_f32 v13, v13, v206, v207
	v_max3_f32 v14, v14, v208, v209
	v_max3_f32 v15, v15, v210, v211
	v_max3_f32 v12, v12, v212, v213
	v_max3_f32 v13, v13, v214, v215
	v_max3_f32 v14, v14, v216, v217
	v_max3_f32 v15, v15, v218, v219
	v_max3_f32 v12, v12, v220, v221
	v_max3_f32 v13, v13, v222, v223
	v_max3_f32 v14, v14, v96, v97
	v_max3_f32 v15, v15, v98, v99
	v_max3_f32 v12, v12, v100, v101
	v_max3_f32 v13, v13, v102, v103
	v_max3_f32 v14, v14, v104, v105
	v_max3_f32 v15, v15, v106, v107
	v_max3_f32 v12, v12, v108, v109
	v_max3_f32 v13, v13, v110, v111
	v_max3_f32 v12, v12, v13, v14
	v_max_f32_e32 v12, v12, v15
	ds_bpermute_b32 v13, v157, v12
	s_waitcnt lgkmcnt(0)
	v_max_f32_e32 v1, v12, v13
	v_sub_f32_e32 v160, v160, v1
	v_sub_f32_e32 v161, v161, v1
	v_sub_f32_e32 v162, v162, v1
	v_sub_f32_e32 v163, v163, v1
	v_sub_f32_e32 v164, v164, v1
	v_sub_f32_e32 v165, v165, v1
	v_sub_f32_e32 v166, v166, v1
	v_sub_f32_e32 v167, v167, v1
	v_sub_f32_e32 v168, v168, v1
	v_sub_f32_e32 v169, v169, v1
	v_sub_f32_e32 v170, v170, v1
	v_sub_f32_e32 v171, v171, v1
	v_sub_f32_e32 v172, v172, v1
	v_sub_f32_e32 v173, v173, v1
	v_sub_f32_e32 v174, v174, v1
	v_sub_f32_e32 v175, v175, v1
	v_sub_f32_e32 v176, v176, v1
	v_sub_f32_e32 v177, v177, v1
	v_sub_f32_e32 v178, v178, v1
	v_sub_f32_e32 v179, v179, v1
	v_sub_f32_e32 v180, v180, v1
	v_sub_f32_e32 v181, v181, v1
	v_sub_f32_e32 v182, v182, v1
	v_sub_f32_e32 v183, v183, v1
	v_sub_f32_e32 v184, v184, v1
	v_sub_f32_e32 v185, v185, v1
	v_sub_f32_e32 v186, v186, v1
	v_sub_f32_e32 v187, v187, v1
	v_sub_f32_e32 v188, v188, v1
	v_sub_f32_e32 v189, v189, v1
	v_sub_f32_e32 v190, v190, v1
	v_sub_f32_e32 v191, v191, v1
	v_sub_f32_e32 v192, v192, v1
	v_sub_f32_e32 v193, v193, v1
	v_sub_f32_e32 v194, v194, v1
	v_sub_f32_e32 v195, v195, v1
	v_sub_f32_e32 v196, v196, v1
	v_sub_f32_e32 v197, v197, v1
	v_sub_f32_e32 v198, v198, v1
	v_sub_f32_e32 v199, v199, v1
	v_sub_f32_e32 v200, v200, v1
	v_sub_f32_e32 v201, v201, v1
	v_sub_f32_e32 v202, v202, v1
	v_sub_f32_e32 v203, v203, v1
	v_sub_f32_e32 v204, v204, v1
	v_sub_f32_e32 v205, v205, v1
	v_sub_f32_e32 v206, v206, v1
	v_sub_f32_e32 v207, v207, v1
	v_sub_f32_e32 v208, v208, v1
	v_sub_f32_e32 v209, v209, v1
	v_sub_f32_e32 v210, v210, v1
	v_sub_f32_e32 v211, v211, v1
	v_sub_f32_e32 v212, v212, v1
	v_sub_f32_e32 v213, v213, v1
	v_sub_f32_e32 v214, v214, v1
	v_sub_f32_e32 v215, v215, v1
	v_sub_f32_e32 v216, v216, v1
	v_sub_f32_e32 v217, v217, v1
	v_sub_f32_e32 v218, v218, v1
	v_sub_f32_e32 v219, v219, v1
	v_sub_f32_e32 v220, v220, v1
	v_sub_f32_e32 v221, v221, v1
	v_sub_f32_e32 v222, v222, v1
	v_sub_f32_e32 v223, v223, v1
	v_sub_f32_e32 v96, v96, v1
	v_sub_f32_e32 v97, v97, v1
	v_sub_f32_e32 v98, v98, v1
	v_sub_f32_e32 v99, v99, v1
	v_sub_f32_e32 v100, v100, v1
	v_sub_f32_e32 v101, v101, v1
	v_sub_f32_e32 v102, v102, v1
	v_sub_f32_e32 v103, v103, v1
	v_sub_f32_e32 v104, v104, v1
	v_sub_f32_e32 v105, v105, v1
	v_sub_f32_e32 v106, v106, v1
	v_sub_f32_e32 v107, v107, v1
	v_sub_f32_e32 v108, v108, v1
	v_sub_f32_e32 v109, v109, v1
	v_sub_f32_e32 v110, v110, v1
	v_sub_f32_e32 v111, v111, v1
	v_exp_f32_e32 v160, v160
	v_exp_f32_e32 v161, v161
	v_exp_f32_e32 v162, v162
	v_exp_f32_e32 v163, v163
	v_exp_f32_e32 v164, v164
	v_exp_f32_e32 v165, v165
	v_exp_f32_e32 v166, v166
	v_exp_f32_e32 v167, v167
	v_exp_f32_e32 v168, v168
	v_exp_f32_e32 v169, v169
	v_exp_f32_e32 v170, v170
	v_exp_f32_e32 v171, v171
	v_exp_f32_e32 v172, v172
	v_exp_f32_e32 v173, v173
	v_exp_f32_e32 v174, v174
	v_exp_f32_e32 v175, v175
	v_exp_f32_e32 v176, v176
	v_exp_f32_e32 v177, v177
	v_exp_f32_e32 v178, v178
	v_exp_f32_e32 v179, v179
	v_exp_f32_e32 v180, v180
	v_exp_f32_e32 v181, v181
	v_exp_f32_e32 v182, v182
	v_exp_f32_e32 v183, v183
	v_exp_f32_e32 v184, v184
	v_exp_f32_e32 v185, v185
	v_exp_f32_e32 v186, v186
	v_exp_f32_e32 v187, v187
	v_exp_f32_e32 v188, v188
	v_exp_f32_e32 v189, v189
	v_exp_f32_e32 v190, v190
	v_exp_f32_e32 v191, v191
	v_exp_f32_e32 v192, v192
	v_exp_f32_e32 v193, v193
	v_exp_f32_e32 v194, v194
	v_exp_f32_e32 v195, v195
	v_exp_f32_e32 v196, v196
	v_exp_f32_e32 v197, v197
	v_exp_f32_e32 v198, v198
	v_exp_f32_e32 v199, v199
	v_exp_f32_e32 v200, v200
	v_exp_f32_e32 v201, v201
	v_exp_f32_e32 v202, v202
	v_exp_f32_e32 v203, v203
	v_exp_f32_e32 v204, v204
	v_exp_f32_e32 v205, v205
	v_exp_f32_e32 v206, v206
	v_exp_f32_e32 v207, v207
	v_exp_f32_e32 v208, v208
	v_exp_f32_e32 v209, v209
	v_exp_f32_e32 v210, v210
	v_exp_f32_e32 v211, v211
	v_exp_f32_e32 v212, v212
	v_exp_f32_e32 v213, v213
	v_exp_f32_e32 v214, v214
	v_exp_f32_e32 v215, v215
	v_exp_f32_e32 v216, v216
	v_exp_f32_e32 v217, v217
	v_exp_f32_e32 v218, v218
	v_exp_f32_e32 v219, v219
	v_exp_f32_e32 v220, v220
	v_exp_f32_e32 v221, v221
	v_exp_f32_e32 v222, v222
	v_exp_f32_e32 v223, v223
	v_exp_f32_e32 v96, v96
	v_exp_f32_e32 v97, v97
	v_exp_f32_e32 v98, v98
	v_exp_f32_e32 v99, v99
	v_exp_f32_e32 v100, v100
	v_exp_f32_e32 v101, v101
	v_exp_f32_e32 v102, v102
	v_exp_f32_e32 v103, v103
	v_exp_f32_e32 v104, v104
	v_exp_f32_e32 v105, v105
	v_exp_f32_e32 v106, v106
	v_exp_f32_e32 v107, v107
	v_exp_f32_e32 v108, v108
	v_exp_f32_e32 v109, v109
	v_exp_f32_e32 v110, v110
	v_exp_f32_e32 v111, v111
	v_add_f32_e32 v12, v160, v161
	v_add_f32_e32 v13, v162, v163
	v_add_f32_e32 v14, v164, v165
	v_add_f32_e32 v15, v166, v167
	v_add_f32_e32 v12, v168, v12
	v_add_f32_e32 v13, v169, v13
	v_add_f32_e32 v14, v170, v14
	v_add_f32_e32 v15, v171, v15
	v_add_f32_e32 v12, v172, v12
	v_add_f32_e32 v13, v173, v13
	v_add_f32_e32 v14, v174, v14
	v_add_f32_e32 v15, v175, v15
	v_add_f32_e32 v12, v176, v12
	v_add_f32_e32 v13, v177, v13
	v_add_f32_e32 v14, v178, v14
	v_add_f32_e32 v15, v179, v15
	v_add_f32_e32 v12, v180, v12
	v_add_f32_e32 v13, v181, v13
	v_add_f32_e32 v14, v182, v14
	v_add_f32_e32 v15, v183, v15
	v_add_f32_e32 v12, v184, v12
	v_add_f32_e32 v13, v185, v13
	v_add_f32_e32 v14, v186, v14
	v_add_f32_e32 v15, v187, v15
	v_add_f32_e32 v12, v188, v12
	v_add_f32_e32 v13, v189, v13
	v_add_f32_e32 v14, v190, v14
	v_add_f32_e32 v15, v191, v15
	v_add_f32_e32 v12, v192, v12
	v_add_f32_e32 v13, v193, v13
	v_add_f32_e32 v14, v194, v14
	v_add_f32_e32 v15, v195, v15
	v_add_f32_e32 v12, v196, v12
	v_add_f32_e32 v13, v197, v13
	v_add_f32_e32 v14, v198, v14
	v_add_f32_e32 v15, v199, v15
	v_add_f32_e32 v12, v200, v12
	v_add_f32_e32 v13, v201, v13
	v_add_f32_e32 v14, v202, v14
	v_add_f32_e32 v15, v203, v15
	v_add_f32_e32 v12, v204, v12
	v_add_f32_e32 v13, v205, v13
	v_add_f32_e32 v14, v206, v14
	v_add_f32_e32 v15, v207, v15
	v_add_f32_e32 v12, v208, v12
	v_add_f32_e32 v13, v209, v13
	v_add_f32_e32 v14, v210, v14
	v_add_f32_e32 v15, v211, v15
	v_add_f32_e32 v12, v212, v12
	v_add_f32_e32 v13, v213, v13
	v_add_f32_e32 v14, v214, v14
	v_add_f32_e32 v15, v215, v15
	v_add_f32_e32 v12, v216, v12
	v_add_f32_e32 v13, v217, v13
	v_add_f32_e32 v14, v218, v14
	v_add_f32_e32 v15, v219, v15
	v_add_f32_e32 v12, v220, v12
	v_add_f32_e32 v13, v221, v13
	v_add_f32_e32 v14, v222, v14
	v_add_f32_e32 v15, v223, v15
	v_add_f32_e32 v12, v96, v12
	v_add_f32_e32 v13, v97, v13
	v_add_f32_e32 v14, v98, v14
	v_add_f32_e32 v15, v99, v15
	v_add_f32_e32 v12, v100, v12
	v_add_f32_e32 v13, v101, v13
	v_add_f32_e32 v14, v102, v14
	v_add_f32_e32 v15, v103, v15
	v_add_f32_e32 v12, v104, v12
	v_add_f32_e32 v13, v105, v13
	v_add_f32_e32 v14, v106, v14
	v_add_f32_e32 v15, v107, v15
	v_add_f32_e32 v12, v108, v12
	v_add_f32_e32 v13, v109, v13
	v_add_f32_e32 v14, v110, v14
	v_add_f32_e32 v15, v111, v15
	v_add_f32_e32 v12, v12, v13
	v_add_f32_e32 v14, v14, v15
	v_add_f32_e32 v6, v12, v14
	v_cvt_pk_bf16_f32 v160, v160, v161
	v_cvt_pk_bf16_f32 v161, v162, v163
	v_cvt_pk_bf16_f32 v162, v164, v165
	v_cvt_pk_bf16_f32 v163, v166, v167
	v_cvt_pk_bf16_f32 v164, v168, v169
	v_cvt_pk_bf16_f32 v165, v170, v171
	v_cvt_pk_bf16_f32 v166, v172, v173
	v_cvt_pk_bf16_f32 v167, v174, v175
	v_cvt_pk_bf16_f32 v176, v176, v177
	v_cvt_pk_bf16_f32 v177, v178, v179
	v_cvt_pk_bf16_f32 v178, v180, v181
	v_cvt_pk_bf16_f32 v179, v182, v183
	v_cvt_pk_bf16_f32 v180, v184, v185
	v_cvt_pk_bf16_f32 v181, v186, v187
	v_cvt_pk_bf16_f32 v182, v188, v189
	v_cvt_pk_bf16_f32 v183, v190, v191
	v_cvt_pk_bf16_f32 v192, v192, v193
	v_cvt_pk_bf16_f32 v193, v194, v195
	v_cvt_pk_bf16_f32 v194, v196, v197
	v_cvt_pk_bf16_f32 v195, v198, v199
	v_cvt_pk_bf16_f32 v196, v200, v201
	v_cvt_pk_bf16_f32 v197, v202, v203
	v_cvt_pk_bf16_f32 v198, v204, v205
	v_cvt_pk_bf16_f32 v199, v206, v207
	v_cvt_pk_bf16_f32 v208, v208, v209
	v_cvt_pk_bf16_f32 v209, v210, v211
	v_cvt_pk_bf16_f32 v210, v212, v213
	v_cvt_pk_bf16_f32 v211, v214, v215
	v_cvt_pk_bf16_f32 v212, v216, v217
	v_cvt_pk_bf16_f32 v213, v218, v219
	v_cvt_pk_bf16_f32 v214, v220, v221
	v_cvt_pk_bf16_f32 v215, v222, v223
	v_cvt_pk_bf16_f32 v96, v96, v97
	v_cvt_pk_bf16_f32 v97, v98, v99
	v_cvt_pk_bf16_f32 v98, v100, v101
	v_cvt_pk_bf16_f32 v99, v102, v103
	v_cvt_pk_bf16_f32 v100, v104, v105
	v_cvt_pk_bf16_f32 v101, v106, v107
	v_cvt_pk_bf16_f32 v102, v108, v109
	v_cvt_pk_bf16_f32 v103, v110, v111
	s_add_i32 s68, s100, 0x8000
	s_add_i32 s69, s68, 0xfffd8000
	s_cmp_ge_i32 s68, 0x28000
	s_cselect_b32 s68, s69, s68
	v_add_u32_e32 v158, s68, v152
	ds_read_b128 v[48:51], v158 offset:4096
	ds_read_b128 v[52:55], v158 offset:5120
	ds_read_b128 v[56:59], v158 offset:6144
	ds_read_b128 v[60:63], v158 offset:7168
	s_waitcnt lgkmcnt(3)
	v_mfma_f32_32x32x16_bf16 v[32:47], v[48:51], v[96:99], 0
	s_waitcnt lgkmcnt(1)
	v_mfma_f32_32x32x16_bf16 v[16:31], v[56:59], v[96:99], 0
	v_mfma_f32_32x32x16_bf16 v[32:47], v[52:55], v[100:103], v[32:47]
	s_waitcnt lgkmcnt(0)
	v_mfma_f32_32x32x16_bf16 v[16:31], v[60:63], v[100:103], v[16:31]
	s_cmp_lt_i32 s85, 4
	s_cbranch_scc1 .La0_pvskip0
	s_add_i32 s68, s100, 0x0
	s_add_i32 s69, s68, 0xfffd8000
	s_cmp_ge_i32 s68, 0x28000
	s_cselect_b32 s68, s69, s68
	v_add_u32_e32 v158, s68, v152
	ds_read_b128 v[224:227], v158 offset:4096
	ds_read_b128 v[228:231], v158 offset:5120
	ds_read_b128 v[2:5], v158 offset:6144
	ds_read_b128 v[8:11], v158 offset:7168
	s_waitcnt lgkmcnt(3)
	v_mfma_f32_32x32x16_bf16 v[32:47], v[224:227], v[160:163], v[32:47]
	s_waitcnt lgkmcnt(1)
	v_mfma_f32_32x32x16_bf16 v[16:31], v[2:5], v[160:163], v[16:31]
	v_mfma_f32_32x32x16_bf16 v[32:47], v[228:231], v[164:167], v[32:47]
	s_waitcnt lgkmcnt(0)
	v_mfma_f32_32x32x16_bf16 v[16:31], v[8:11], v[164:167], v[16:31]
.La0_pvskip0:
	s_cmp_lt_i32 s85, 3
	s_cbranch_scc1 .La0_pvskip1
	s_add_i32 s68, s100, 0x2000
	s_add_i32 s69, s68, 0xfffd8000
	s_cmp_ge_i32 s68, 0x28000
	s_cselect_b32 s68, s69, s68
	v_add_u32_e32 v158, s68, v152
	ds_read_b128 v[48:51], v158 offset:4096
	ds_read_b128 v[52:55], v158 offset:5120
	ds_read_b128 v[56:59], v158 offset:6144
	ds_read_b128 v[60:63], v158 offset:7168
	s_waitcnt lgkmcnt(3)
	v_mfma_f32_32x32x16_bf16 v[32:47], v[48:51], v[176:179], v[32:47]
	s_waitcnt lgkmcnt(1)
	v_mfma_f32_32x32x16_bf16 v[16:31], v[56:59], v[176:179], v[16:31]
	v_mfma_f32_32x32x16_bf16 v[32:47], v[52:55], v[180:183], v[32:47]
	s_waitcnt lgkmcnt(0)
	v_mfma_f32_32x32x16_bf16 v[16:31], v[60:63], v[180:183], v[16:31]
.La0_pvskip1:
	s_cmp_lt_i32 s85, 2
	s_cbranch_scc1 .La0_pvskip2
	s_add_i32 s68, s100, 0x4000
	s_add_i32 s69, s68, 0xfffd8000
	s_cmp_ge_i32 s68, 0x28000
	s_cselect_b32 s68, s69, s68
	v_add_u32_e32 v158, s68, v152
	ds_read_b128 v[224:227], v158 offset:4096
	ds_read_b128 v[228:231], v158 offset:5120
	ds_read_b128 v[2:5], v158 offset:6144
	ds_read_b128 v[8:11], v158 offset:7168
	s_waitcnt lgkmcnt(3)
	v_mfma_f32_32x32x16_bf16 v[32:47], v[224:227], v[192:195], v[32:47]
	s_waitcnt lgkmcnt(1)
	v_mfma_f32_32x32x16_bf16 v[16:31], v[2:5], v[192:195], v[16:31]
	v_mfma_f32_32x32x16_bf16 v[32:47], v[228:231], v[196:199], v[32:47]
	s_waitcnt lgkmcnt(0)
	v_mfma_f32_32x32x16_bf16 v[16:31], v[8:11], v[196:199], v[16:31]
.La0_pvskip2:
	s_cmp_lt_i32 s85, 1
	s_cbranch_scc1 .La0_pvskip3
	s_add_i32 s68, s100, 0x6000
	s_add_i32 s69, s68, 0xfffd8000
	s_cmp_ge_i32 s68, 0x28000
	s_cselect_b32 s68, s69, s68
	v_add_u32_e32 v158, s68, v152
	ds_read_b128 v[48:51], v158 offset:4096
	ds_read_b128 v[52:55], v158 offset:5120
	ds_read_b128 v[56:59], v158 offset:6144
	ds_read_b128 v[60:63], v158 offset:7168
	s_waitcnt lgkmcnt(3)
	v_mfma_f32_32x32x16_bf16 v[32:47], v[48:51], v[208:211], v[32:47]
	s_waitcnt lgkmcnt(1)
	v_mfma_f32_32x32x16_bf16 v[16:31], v[56:59], v[208:211], v[16:31]
	v_mfma_f32_32x32x16_bf16 v[32:47], v[52:55], v[212:215], v[32:47]
	s_waitcnt lgkmcnt(0)
	v_mfma_f32_32x32x16_bf16 v[16:31], v[60:63], v[212:215], v[16:31]

.LBB0_466:
	s_cmp_lg_u32 s95, 7
	s_cbranch_scc1 .La0_ep
	s_waitcnt vmcnt(0)
.La0_ep:
	v_cmp_lt_i32_e32 vcc, v155, v156
	v_cndmask_b32_e64 v4, 0, 1, s[88:89]
	v_cmp_ne_u32_e64 s[68:69], 1, v4
	v_cndmask_b32_e32 v2, v68, v155, vcc
	v_lshlrev_b32_e32 v2, 2, v2
	ds_bpermute_b32 v2, v2, v6
	s_andn2_b64 vcc, exec, s[88:89]
	s_waitcnt lgkmcnt(0)
	v_add_f32_e32 v3, v6, v2
	v_rcp_f32_e32 v2, v3
	v_log_f32_e32 v3, v3
	s_nop 0
	v_add_f32_e32 v1, v1, v3
	s_cbranch_vccnz .LBB0_485
	v_max_f32_e32 v3, v1, v1
	s_waitcnt vmcnt(20)
	v_max_f32_e32 v4, v154, v154
	v_max_f32_e32 v6, v4, v3
	v_sub_f32_e32 v1, v1, v6
	v_sub_f32_e32 v3, v154, v6
	v_exp_f32_e32 v1, v1
	v_exp_f32_e32 v3, v3
	s_nop 0
	v_add_f32_e32 v4, v1, v3
	v_rcp_f32_e32 v5, v4
	v_log_f32_e32 v7, v4
	v_mul_f32_e32 v4, v1, v5
	v_pk_mul_f32 v[2:3], v[2:3], v[4:5]
	v_add_f32_e32 v1, v6, v7
	v_pk_mul_f32 v[6:7], v[32:33], v[2:3] op_sel_hi:[1,0]
	s_and_b64 vcc, exec, s[68:69]
	v_pk_mul_f32 v[8:9], v[34:35], v[2:3] op_sel_hi:[1,0]
	s_cbranch_vccnz .LBB0_469
.LBB0_468:
	s_waitcnt vmcnt(19)
	v_lshlrev_b32_e32 v4, 16, v138
	v_and_b32_e32 v5, 0xffff0000, v138
	v_pk_fma_f32 v[6:7], v[2:3], v[4:5], v[6:7] op_sel:[1,0,0]
	v_lshlrev_b32_e32 v4, 16, v139
	v_and_b32_e32 v5, 0xffff0000, v139
	v_pk_fma_f32 v[8:9], v[2:3], v[4:5], v[8:9] op_sel:[1,0,0]
.LBB0_469:
	v_mov_b32_e32 v4, v2
	v_mov_b32_e32 v5, v2
	v_cvt_pk_bf16_f32 v6, v6, v7
	v_cvt_pk_bf16_f32 v7, v8, v9
	global_store_dwordx2 v[148:149], v[6:7], off
	v_pk_mul_f32 v[6:7], v[36:37], v[4:5]
	s_and_b64 vcc, exec, s[68:69]
	v_pk_mul_f32 v[8:9], v[38:39], v[4:5]
	s_cbranch_vccnz .LBB0_471
	s_waitcnt vmcnt(19)
	v_lshlrev_b32_e32 v10, 16, v136
	v_and_b32_e32 v11, 0xffff0000, v136
	v_pk_fma_f32 v[6:7], v[2:3], v[10:11], v[6:7] op_sel:[1,0,0]
	v_lshlrev_b32_e32 v10, 16, v137
	v_and_b32_e32 v11, 0xffff0000, v137
	v_pk_fma_f32 v[8:9], v[2:3], v[10:11], v[8:9] op_sel:[1,0,0]
.LBB0_471:
	v_cvt_pk_bf16_f32 v6, v6, v7
	v_cvt_pk_bf16_f32 v7, v8, v9
	global_store_dwordx2 v[148:149], v[6:7], off offset:16
	v_pk_mul_f32 v[6:7], v[40:41], v[4:5]
	s_and_b64 vcc, exec, s[68:69]
	v_pk_mul_f32 v[8:9], v[42:43], v[4:5]
	s_cbranch_vccnz .LBB0_473
	s_waitcnt vmcnt(19)
	v_lshlrev_b32_e32 v10, 16, v134
	v_and_b32_e32 v11, 0xffff0000, v134
	v_pk_fma_f32 v[6:7], v[2:3], v[10:11], v[6:7] op_sel:[1,0,0]
	v_lshlrev_b32_e32 v10, 16, v135
	v_and_b32_e32 v11, 0xffff0000, v135
	v_pk_fma_f32 v[8:9], v[2:3], v[10:11], v[8:9] op_sel:[1,0,0]
.LBB0_473:
	v_cvt_pk_bf16_f32 v6, v6, v7
	v_cvt_pk_bf16_f32 v7, v8, v9
	global_store_dwordx2 v[148:149], v[6:7], off offset:32
	v_pk_mul_f32 v[6:7], v[44:45], v[4:5]
	s_and_b64 vcc, exec, s[68:69]
	v_pk_mul_f32 v[8:9], v[46:47], v[4:5]
	s_cbranch_vccnz .LBB0_475
	s_waitcnt vmcnt(19)
	v_lshlrev_b32_e32 v10, 16, v132
	v_and_b32_e32 v11, 0xffff0000, v132
	v_pk_fma_f32 v[6:7], v[2:3], v[10:11], v[6:7] op_sel:[1,0,0]
	v_lshlrev_b32_e32 v10, 16, v133
	v_and_b32_e32 v11, 0xffff0000, v133
	v_pk_fma_f32 v[8:9], v[2:3], v[10:11], v[8:9] op_sel:[1,0,0]
.LBB0_475:
	v_cvt_pk_bf16_f32 v6, v6, v7
	v_cvt_pk_bf16_f32 v7, v8, v9
	global_store_dwordx2 v[148:149], v[6:7], off offset:48
	v_pk_mul_f32 v[6:7], v[16:17], v[4:5]
	s_and_b64 vcc, exec, s[68:69]
	v_pk_mul_f32 v[8:9], v[18:19], v[4:5]
	s_cbranch_vccnz .LBB0_477
	s_waitcnt vmcnt(19)
	v_lshlrev_b32_e32 v10, 16, v130
	v_and_b32_e32 v11, 0xffff0000, v130
	v_pk_fma_f32 v[6:7], v[2:3], v[10:11], v[6:7] op_sel:[1,0,0]
	v_lshlrev_b32_e32 v10, 16, v131
	v_and_b32_e32 v11, 0xffff0000, v131
	v_pk_fma_f32 v[8:9], v[2:3], v[10:11], v[8:9] op_sel:[1,0,0]
.LBB0_477:
	v_cvt_pk_bf16_f32 v6, v6, v7
	v_cvt_pk_bf16_f32 v7, v8, v9
	global_store_dwordx2 v[148:149], v[6:7], off offset:64
	v_pk_mul_f32 v[6:7], v[20:21], v[4:5]
	s_and_b64 vcc, exec, s[68:69]
	v_pk_mul_f32 v[8:9], v[22:23], v[4:5]
	s_cbranch_vccnz .LBB0_479
	s_waitcnt vmcnt(19)
	v_lshlrev_b32_e32 v10, 16, v128
	v_and_b32_e32 v11, 0xffff0000, v128
	v_pk_fma_f32 v[6:7], v[2:3], v[10:11], v[6:7] op_sel:[1,0,0]
	v_lshlrev_b32_e32 v10, 16, v129
	v_and_b32_e32 v11, 0xffff0000, v129
	v_pk_fma_f32 v[8:9], v[2:3], v[10:11], v[8:9] op_sel:[1,0,0]
.LBB0_479:
	v_cvt_pk_bf16_f32 v6, v6, v7
	v_cvt_pk_bf16_f32 v7, v8, v9
	global_store_dwordx2 v[148:149], v[6:7], off offset:80
	v_pk_mul_f32 v[6:7], v[24:25], v[4:5]
	s_and_b64 vcc, exec, s[68:69]
	v_pk_mul_f32 v[8:9], v[26:27], v[4:5]
	s_cbranch_vccnz .LBB0_481
	s_waitcnt vmcnt(19)
	v_lshlrev_b32_e32 v10, 16, v126
	v_and_b32_e32 v11, 0xffff0000, v126
	v_pk_fma_f32 v[6:7], v[2:3], v[10:11], v[6:7] op_sel:[1,0,0]
	v_lshlrev_b32_e32 v10, 16, v127
	v_and_b32_e32 v11, 0xffff0000, v127
	v_pk_fma_f32 v[8:9], v[2:3], v[10:11], v[8:9] op_sel:[1,0,0]
.LBB0_481:
	v_cvt_pk_bf16_f32 v6, v6, v7
	v_cvt_pk_bf16_f32 v7, v8, v9
	global_store_dwordx2 v[148:149], v[6:7], off offset:96
	v_pk_mul_f32 v[6:7], v[28:29], v[4:5]
	s_and_b64 vcc, exec, s[68:69]
	v_pk_mul_f32 v[4:5], v[30:31], v[4:5]
	s_cbranch_vccnz .LBB0_483
	s_waitcnt vmcnt(19)
	v_lshlrev_b32_e32 v8, 16, v124
	v_and_b32_e32 v9, 0xffff0000, v124
	v_pk_fma_f32 v[6:7], v[2:3], v[8:9], v[6:7] op_sel:[1,0,0]
	v_lshlrev_b32_e32 v8, 16, v125
	v_and_b32_e32 v9, 0xffff0000, v125
	v_pk_fma_f32 v[4:5], v[2:3], v[8:9], v[4:5] op_sel:[1,0,0]

.LBB0_486:
	s_waitcnt vmcnt(0) lgkmcnt(0)
	s_barrier
	s_cmp_lg_u32 s71, 0
	s_cbranch_scc1 .La0_norest
	ds_write_b32 v251, v250
	s_waitcnt lgkmcnt(0)
.La0_norest:
	s_barrier
	v_readlane_b32 s82, v255, 22
	v_readlane_b32 s92, v255, 10
	v_readlane_b32 s72, v254, 10
	v_readlane_b32 s62, v255, 13
	v_readlane_b32 s63, v255, 14
	s_mov_b32 s64, 0xf800000
	v_readlane_b32 s65, v255, 15
	s_mov_b32 s66, 0xbfb8aa3b
	s_mov_b32 s67, 0x1fffe0
	s_movk_i32 s68, 0xb00
	s_movk_i32 s69, 0x1600
	s_movk_i32 s73, 0x161
	v_readlane_b32 s74, v255, 16
	v_readlane_b32 s75, v255, 20
	v_readlane_b32 s76, v255, 19
	v_readlane_b32 s83, v255, 23
	v_readlane_b32 s10, v255, 28
	v_readlane_b32 s7, v255, 21

	.amdhsa_kernel _Z8mega_fwd4Args
		.amdhsa_group_segment_fixed_size 16384
		.amdhsa_private_segment_fixed_size 0
		.amdhsa_kernarg_size 376
		.amdhsa_user_sgpr_count 2
		.amdhsa_user_sgpr_dispatch_ptr 0
		.amdhsa_user_sgpr_queue_ptr 0
		.amdhsa_user_sgpr_kernarg_segment_ptr 1
		.amdhsa_user_sgpr_dispatch_id 0
		.amdhsa_user_sgpr_kernarg_preload_length 0
		.amdhsa_user_sgpr_kernarg_preload_offset 0
		.amdhsa_user_sgpr_private_segment_size 0
		.amdhsa_uses_dynamic_stack 0
		.amdhsa_enable_private_segment 0
		.amdhsa_system_sgpr_workgroup_id_x 1
		.amdhsa_system_sgpr_workgroup_id_y 0
		.amdhsa_system_sgpr_workgroup_id_z 0
		.amdhsa_system_sgpr_workgroup_info 0
		.amdhsa_system_vgpr_workitem_id 2
		.amdhsa_next_free_vgpr 256
		.amdhsa_next_free_sgpr 102
		.amdhsa_accum_offset 256
		.amdhsa_reserve_vcc 1
		.amdhsa_float_round_mode_32 0
		.amdhsa_float_round_mode_16_64 0
		.amdhsa_float_denorm_mode_32 3
		.amdhsa_float_denorm_mode_16_64 3
		.amdhsa_dx10_clamp 1
		.amdhsa_ieee_mode 1
		.amdhsa_fp16_overflow 0
		.amdhsa_tg_split 0
		.amdhsa_exception_fp_ieee_invalid_op 0
		.amdhsa_exception_fp_denorm_src 0
		.amdhsa_exception_fp_ieee_div_zero 0
		.amdhsa_exception_fp_ieee_overflow 0
		.amdhsa_exception_fp_ieee_underflow 0
		.amdhsa_exception_fp_ieee_inexact 0
		.amdhsa_exception_int_div_zero 0
	.end_amdhsa_kernel

amdhsa.kernels:
  - .agpr_count:     0
    .args:
      - .offset:         0
        .size:           120
        .value_kind:     by_value
      - .offset:         120
        .size:           4
        .value_kind:     hidden_block_count_x
      - .offset:         124
        .size:           4
        .value_kind:     hidden_block_count_y
      - .offset:         128
        .size:           4
        .value_kind:     hidden_block_count_z
      - .offset:         132
        .size:           2
        .value_kind:     hidden_group_size_x
      - .offset:         134
        .size:           2
        .value_kind:     hidden_group_size_y
      - .offset:         136
        .size:           2
        .value_kind:     hidden_group_size_z
      - .offset:         138
        .size:           2
        .value_kind:     hidden_remainder_x
      - .offset:         140
        .size:           2
        .value_kind:     hidden_remainder_y
      - .offset:         142
        .size:           2
        .value_kind:     hidden_remainder_z
      - .offset:         160
        .size:           8
        .value_kind:     hidden_global_offset_x
      - .offset:         168
        .size:           8
        .value_kind:     hidden_global_offset_y
      - .offset:         176
        .size:           8
        .value_kind:     hidden_global_offset_z
      - .offset:         184
        .size:           2
        .value_kind:     hidden_grid_dims
      - .offset:         208
        .size:           8
        .value_kind:     hidden_multigrid_sync_arg
      - .offset:         240
        .size:           4
        .value_kind:     hidden_dynamic_lds_size
    .group_segment_fixed_size: 16384
    .kernarg_segment_align: 8
    .kernarg_segment_size: 376
    .language:       OpenCL C
    .language_version:
      - 2
      - 0
    .max_flat_workgroup_size: 512
    .name:           _Z8mega_fwd4Args
    .private_segment_fixed_size: 0
    .sgpr_count:     108
    .sgpr_spill_count: 95
    .symbol:         _Z8mega_fwd4Args.kd
    .uniform_work_group_size: 1
    .uses_dynamic_stack: false
    .vgpr_count:     256
    .vgpr_spill_count: 0
    .wavefront_size: 64
